# grid barrier poll loops without s_sleep (tighter polling of the GO word)
# speedup vs baseline: 1.0077x; 1.0045x over previous
.Lxb1_poll:
	global_load_dword v10, v8, s[70:71] offset:1024 sc1
	s_add_i32 s10, s10, 1
	s_waitcnt vmcnt(0)
	v_cmp_ge_u32_e32 vcc, v10, v11
	s_cbranch_vccnz .Lxb1_done
	s_cmp_lt_u32 s10, 0x8000
	s_cbranch_scc1 .Lxb1_poll
